# in-proj plain-path epilogue (xa,ya,u): permlane16_swap pairs then 16 dwordx4 stores per tile instead of 32 dwordx2
# speedup vs baseline: 1.0063x; 1.0045x over previous
; template <int EPI>
; __device__ __forceinline__ void gemm_epilogue(const f32x4 (&acc)[2][2][4][2], const Unit& u, int wr, int wc, int fr, int fq,
;                                               const EpiArgs& ea, const float (&rs_pre)[2][4]) {
;     ...
;     if (plain) {
; #pragma unroll
;       for (int ai = 0; ai < 2; ++ai)
; #pragma unroll
;         for (int m = 0; m < 4; ++m) {
;           const int row = row0 + ai * 128 + m * 16;
;           const float rs = rsr[ai][m];
; #pragma unroll
;           for (int bj = 0; bj < 2; ++bj)
; #pragma unroll
;             for (int n = 0; n < 2; ++n)
;               *reinterpret_cast<uint2*>(ea.out_bf + (size_t)row * LD + lc0 + bj * 32 + n * 16) = pack4(acc[ai][bj][m][n] * rs);
;         }
.LBB0_618:
	s_andn2_b64 vcc, exec, s[0:1]
	s_cbranch_vccnz .LBB0_569
	v_mbcnt_lo_u32_b32 v133, -1, 0
	v_mbcnt_hi_u32_b32 v133, -1, v133
	v_and_b32_e32 v133, 16, v133
	v_lshrrev_b32_e32 v132, 1, v133
	v_add_u32_e32 v132, v132, v133
	v_lshl_add_u32 v132, v178, 1, v132
	v_pk_mul_f32 v[126:127], v[126:127], v[176:177] op_sel_hi:[1,0]
	v_pk_mul_f32 v[128:129], v[128:129], v[176:177] op_sel_hi:[1,0]
	v_pk_mul_f32 v[122:123], v[122:123], v[176:177] op_sel_hi:[1,0]
	v_pk_mul_f32 v[124:125], v[124:125], v[176:177] op_sel_hi:[1,0]
	v_pk_mul_f32 v[118:119], v[118:119], v[176:177] op_sel_hi:[1,0]
	v_pk_mul_f32 v[120:121], v[120:121], v[176:177] op_sel_hi:[1,0]
	v_pk_mul_f32 v[114:115], v[114:115], v[176:177] op_sel_hi:[1,0]
	v_pk_mul_f32 v[116:117], v[116:117], v[176:177] op_sel_hi:[1,0]
	v_mul_lo_u32 v131, v172, s45
	v_cvt_pk_bf16_f32 v126, v126, v127
	v_cvt_pk_bf16_f32 v127, v128, v129
	v_cvt_pk_bf16_f32 v128, v122, v123
	v_cvt_pk_bf16_f32 v129, v124, v125
	v_cvt_pk_bf16_f32 v118, v118, v119
	v_cvt_pk_bf16_f32 v119, v120, v121
	v_cvt_pk_bf16_f32 v120, v114, v115
	v_cvt_pk_bf16_f32 v121, v116, v117
	v_add_u32_e32 v131, v131, v132
	v_permlane16_swap_b32_e32 v126, v128
	v_permlane16_swap_b32_e32 v127, v129
	v_permlane16_swap_b32_e32 v118, v120
	v_permlane16_swap_b32_e32 v119, v121
	global_store_dwordx4 v131, v[126:129], s[42:43]
	global_store_dwordx4 v131, v[118:121], s[42:43] offset:64
	v_pk_mul_f32 v[108:109], v[108:109], v[174:175] op_sel_hi:[1,0]
	v_pk_mul_f32 v[110:111], v[110:111], v[174:175] op_sel_hi:[1,0]
	v_pk_mul_f32 v[104:105], v[104:105], v[174:175] op_sel_hi:[1,0]
	v_pk_mul_f32 v[106:107], v[106:107], v[174:175] op_sel_hi:[1,0]
	v_pk_mul_f32 v[100:101], v[100:101], v[174:175] op_sel_hi:[1,0]
	v_pk_mul_f32 v[102:103], v[102:103], v[174:175] op_sel_hi:[1,0]
	v_pk_mul_f32 v[96:97], v[96:97], v[174:175] op_sel_hi:[1,0]
	v_pk_mul_f32 v[98:99], v[98:99], v[174:175] op_sel_hi:[1,0]
	v_mul_lo_u32 v131, v168, s45
	v_cvt_pk_bf16_f32 v108, v108, v109
	v_cvt_pk_bf16_f32 v109, v110, v111
	v_cvt_pk_bf16_f32 v110, v104, v105
	v_cvt_pk_bf16_f32 v111, v106, v107
	v_cvt_pk_bf16_f32 v100, v100, v101
	v_cvt_pk_bf16_f32 v101, v102, v103
	v_cvt_pk_bf16_f32 v102, v96, v97
	v_cvt_pk_bf16_f32 v103, v98, v99
	v_add_u32_e32 v131, v131, v132
	v_permlane16_swap_b32_e32 v108, v110
	v_permlane16_swap_b32_e32 v109, v111
	v_permlane16_swap_b32_e32 v100, v102
	v_permlane16_swap_b32_e32 v101, v103
	global_store_dwordx4 v131, v[108:111], s[42:43]
	global_store_dwordx4 v131, v[100:103], s[42:43] offset:64
	v_pk_mul_f32 v[92:93], v[92:93], v[170:171] op_sel_hi:[1,0]
	v_pk_mul_f32 v[94:95], v[94:95], v[170:171] op_sel_hi:[1,0]
	v_pk_mul_f32 v[88:89], v[88:89], v[170:171] op_sel_hi:[1,0]
	v_pk_mul_f32 v[90:91], v[90:91], v[170:171] op_sel_hi:[1,0]
	v_pk_mul_f32 v[84:85], v[84:85], v[170:171] op_sel_hi:[1,0]
	v_pk_mul_f32 v[86:87], v[86:87], v[170:171] op_sel_hi:[1,0]
	v_pk_mul_f32 v[80:81], v[80:81], v[170:171] op_sel_hi:[1,0]
	v_pk_mul_f32 v[82:83], v[82:83], v[170:171] op_sel_hi:[1,0]
	v_mul_lo_u32 v131, v164, s45
	v_cvt_pk_bf16_f32 v92, v92, v93
	v_cvt_pk_bf16_f32 v93, v94, v95
	v_cvt_pk_bf16_f32 v94, v88, v89
	v_cvt_pk_bf16_f32 v95, v90, v91
	v_cvt_pk_bf16_f32 v84, v84, v85
	v_cvt_pk_bf16_f32 v85, v86, v87
	v_cvt_pk_bf16_f32 v86, v80, v81
	v_cvt_pk_bf16_f32 v87, v82, v83
	v_add_u32_e32 v131, v131, v132
	v_permlane16_swap_b32_e32 v92, v94
	v_permlane16_swap_b32_e32 v93, v95
	v_permlane16_swap_b32_e32 v84, v86
	v_permlane16_swap_b32_e32 v85, v87
	global_store_dwordx4 v131, v[92:95], s[42:43]
	global_store_dwordx4 v131, v[84:87], s[42:43] offset:64
	v_pk_mul_f32 v[76:77], v[76:77], v[166:167] op_sel_hi:[1,0]
	v_pk_mul_f32 v[78:79], v[78:79], v[166:167] op_sel_hi:[1,0]
	v_pk_mul_f32 v[72:73], v[72:73], v[166:167] op_sel_hi:[1,0]
	v_pk_mul_f32 v[74:75], v[74:75], v[166:167] op_sel_hi:[1,0]
	v_pk_mul_f32 v[68:69], v[68:69], v[166:167] op_sel_hi:[1,0]
	v_pk_mul_f32 v[70:71], v[70:71], v[166:167] op_sel_hi:[1,0]
	v_pk_mul_f32 v[64:65], v[64:65], v[166:167] op_sel_hi:[1,0]
	v_pk_mul_f32 v[66:67], v[66:67], v[166:167] op_sel_hi:[1,0]
	v_mul_lo_u32 v131, v160, s45
	v_cvt_pk_bf16_f32 v76, v76, v77
	v_cvt_pk_bf16_f32 v77, v78, v79
	v_cvt_pk_bf16_f32 v78, v72, v73
	v_cvt_pk_bf16_f32 v79, v74, v75
	v_cvt_pk_bf16_f32 v68, v68, v69
	v_cvt_pk_bf16_f32 v69, v70, v71
	v_cvt_pk_bf16_f32 v70, v64, v65
	v_cvt_pk_bf16_f32 v71, v66, v67
	v_add_u32_e32 v131, v131, v132
	v_permlane16_swap_b32_e32 v76, v78
; template <int EPI>
; __device__ __forceinline__ void gemm_epilogue(const f32x4 (&acc)[2][2][4][2], const Unit& u, int wr, int wc, int fr, int fq,
;                                               const EpiArgs& ea, const float (&rs_pre)[2][4]) {
;     ...
;     if (plain) {
; #pragma unroll
;       for (int ai = 0; ai < 2; ++ai)
; #pragma unroll
;         for (int m = 0; m < 4; ++m) {
;           const int row = row0 + ai * 128 + m * 16;
;           const float rs = rsr[ai][m];
; #pragma unroll
;           for (int bj = 0; bj < 2; ++bj)
; #pragma unroll
;             for (int n = 0; n < 2; ++n)
;               *reinterpret_cast<uint2*>(ea.out_bf + (size_t)row * LD + lc0 + bj * 32 + n * 16) = pack4(acc[ai][bj][m][n] * rs);
;         }
	v_permlane16_swap_b32_e32 v77, v79
	v_permlane16_swap_b32_e32 v68, v70
	v_permlane16_swap_b32_e32 v69, v71
	global_store_dwordx4 v131, v[76:79], s[42:43]
	global_store_dwordx4 v131, v[68:71], s[42:43] offset:64
	v_pk_mul_f32 v[60:61], v[60:61], v[162:163] op_sel_hi:[1,0]
	v_pk_mul_f32 v[62:63], v[62:63], v[162:163] op_sel_hi:[1,0]
	v_pk_mul_f32 v[56:57], v[56:57], v[162:163] op_sel_hi:[1,0]
	v_pk_mul_f32 v[58:59], v[58:59], v[162:163] op_sel_hi:[1,0]
	v_pk_mul_f32 v[52:53], v[52:53], v[162:163] op_sel_hi:[1,0]
	v_pk_mul_f32 v[54:55], v[54:55], v[162:163] op_sel_hi:[1,0]
	v_pk_mul_f32 v[48:49], v[48:49], v[162:163] op_sel_hi:[1,0]
	v_pk_mul_f32 v[50:51], v[50:51], v[162:163] op_sel_hi:[1,0]
	v_mul_lo_u32 v131, v167, s45
	v_cvt_pk_bf16_f32 v60, v60, v61
	v_cvt_pk_bf16_f32 v61, v62, v63
	v_cvt_pk_bf16_f32 v62, v56, v57
	v_cvt_pk_bf16_f32 v63, v58, v59
	v_cvt_pk_bf16_f32 v52, v52, v53
	v_cvt_pk_bf16_f32 v53, v54, v55
	v_cvt_pk_bf16_f32 v54, v48, v49
	v_cvt_pk_bf16_f32 v55, v50, v51
	v_add_u32_e32 v131, v131, v132
	v_permlane16_swap_b32_e32 v60, v62
	v_permlane16_swap_b32_e32 v61, v63
	v_permlane16_swap_b32_e32 v52, v54
	v_permlane16_swap_b32_e32 v53, v55
	global_store_dwordx4 v131, v[60:63], s[42:43]
	global_store_dwordx4 v131, v[52:55], s[42:43] offset:64
	v_pk_mul_f32 v[44:45], v[44:45], v[158:159] op_sel_hi:[1,0]
	v_pk_mul_f32 v[46:47], v[46:47], v[158:159] op_sel_hi:[1,0]
	v_pk_mul_f32 v[40:41], v[40:41], v[158:159] op_sel_hi:[1,0]
	v_pk_mul_f32 v[42:43], v[42:43], v[158:159] op_sel_hi:[1,0]
	v_pk_mul_f32 v[36:37], v[36:37], v[158:159] op_sel_hi:[1,0]
	v_pk_mul_f32 v[38:39], v[38:39], v[158:159] op_sel_hi:[1,0]
	v_pk_mul_f32 v[32:33], v[32:33], v[158:159] op_sel_hi:[1,0]
	v_pk_mul_f32 v[34:35], v[34:35], v[158:159] op_sel_hi:[1,0]
	v_mul_lo_u32 v131, v165, s45
	v_cvt_pk_bf16_f32 v44, v44, v45
	v_cvt_pk_bf16_f32 v45, v46, v47
	v_cvt_pk_bf16_f32 v46, v40, v41
	v_cvt_pk_bf16_f32 v47, v42, v43
	v_cvt_pk_bf16_f32 v36, v36, v37
	v_cvt_pk_bf16_f32 v37, v38, v39
	v_cvt_pk_bf16_f32 v38, v32, v33
	v_cvt_pk_bf16_f32 v39, v34, v35
	v_add_u32_e32 v131, v131, v132
	v_permlane16_swap_b32_e32 v44, v46
	v_permlane16_swap_b32_e32 v45, v47
	v_permlane16_swap_b32_e32 v36, v38
	v_permlane16_swap_b32_e32 v37, v39
	global_store_dwordx4 v131, v[44:47], s[42:43]
	global_store_dwordx4 v131, v[36:39], s[42:43] offset:64
	v_pk_mul_f32 v[28:29], v[28:29], v[156:157] op_sel_hi:[1,0]
	v_pk_mul_f32 v[30:31], v[30:31], v[156:157] op_sel_hi:[1,0]
	v_pk_mul_f32 v[24:25], v[24:25], v[156:157] op_sel_hi:[1,0]
	v_pk_mul_f32 v[26:27], v[26:27], v[156:157] op_sel_hi:[1,0]
	v_pk_mul_f32 v[20:21], v[20:21], v[156:157] op_sel_hi:[1,0]
	v_pk_mul_f32 v[22:23], v[22:23], v[156:157] op_sel_hi:[1,0]
	v_pk_mul_f32 v[16:17], v[16:17], v[156:157] op_sel_hi:[1,0]
	v_pk_mul_f32 v[18:19], v[18:19], v[156:157] op_sel_hi:[1,0]
	v_mul_lo_u32 v131, v163, s45
	v_cvt_pk_bf16_f32 v28, v28, v29
	v_cvt_pk_bf16_f32 v29, v30, v31
	v_cvt_pk_bf16_f32 v30, v24, v25
	v_cvt_pk_bf16_f32 v31, v26, v27
	v_cvt_pk_bf16_f32 v20, v20, v21
	v_cvt_pk_bf16_f32 v21, v22, v23
	v_cvt_pk_bf16_f32 v22, v16, v17
	v_cvt_pk_bf16_f32 v23, v18, v19
	v_add_u32_e32 v131, v131, v132
	v_permlane16_swap_b32_e32 v28, v30
	v_permlane16_swap_b32_e32 v29, v31
	v_permlane16_swap_b32_e32 v20, v22
	v_permlane16_swap_b32_e32 v21, v23
	global_store_dwordx4 v131, v[28:31], s[42:43]
	global_store_dwordx4 v131, v[20:23], s[42:43] offset:64
	v_pk_mul_f32 v[12:13], v[12:13], v[154:155] op_sel_hi:[1,0]
	v_pk_mul_f32 v[14:15], v[14:15], v[154:155] op_sel_hi:[1,0]
	v_pk_mul_f32 v[8:9], v[8:9], v[154:155] op_sel_hi:[1,0]
	v_pk_mul_f32 v[10:11], v[10:11], v[154:155] op_sel_hi:[1,0]
	v_pk_mul_f32 v[4:5], v[4:5], v[154:155] op_sel_hi:[1,0]
	v_pk_mul_f32 v[6:7], v[6:7], v[154:155] op_sel_hi:[1,0]
	v_pk_mul_f32 v[0:1], v[0:1], v[154:155] op_sel_hi:[1,0]
	v_pk_mul_f32 v[2:3], v[2:3], v[154:155] op_sel_hi:[1,0]
	v_mul_lo_u32 v131, v161, s45
	v_cvt_pk_bf16_f32 v12, v12, v13
	v_cvt_pk_bf16_f32 v13, v14, v15
	v_cvt_pk_bf16_f32 v14, v8, v9
	v_cvt_pk_bf16_f32 v15, v10, v11
	v_cvt_pk_bf16_f32 v4, v4, v5
	v_cvt_pk_bf16_f32 v5, v6, v7
	v_cvt_pk_bf16_f32 v6, v0, v1
	v_cvt_pk_bf16_f32 v7, v2, v3
	v_add_u32_e32 v131, v131, v132
	v_permlane16_swap_b32_e32 v12, v14
	v_permlane16_swap_b32_e32 v13, v15
	v_permlane16_swap_b32_e32 v4, v6
	v_permlane16_swap_b32_e32 v5, v7
	global_store_dwordx4 v131, v[12:15], s[42:43]
	global_store_dwordx4 v131, v[4:7], s[42:43] offset:64
	s_branch .LBB0_569

; template <int EPI>
; __device__ __forceinline__ void gemm_epilogue(const f32x4 (&acc)[2][2][4][2], const Unit& u, int wr, int wc, int fr, int fq,
;                                               const EpiArgs& ea, const float (&rs_pre)[2][4]) {
;     ...
;     if (plain) {
; #pragma unroll
;       for (int ai = 0; ai < 2; ++ai)
; #pragma unroll
;         for (int m = 0; m < 4; ++m) {
;           const int row = row0 + ai * 128 + m * 16;
;           const float rs = rsr[ai][m];
; #pragma unroll
;           for (int bj = 0; bj < 2; ++bj)
; #pragma unroll
;             for (int n = 0; n < 2; ++n)
;               *reinterpret_cast<uint2*>(ea.out_bf + (size_t)row * LD + lc0 + bj * 32 + n * 16) = pack4(acc[ai][bj][m][n] * rs);
;         }
.LBB0_739:
	s_andn2_b64 vcc, exec, s[4:5]
	s_cbranch_vccnz .LBB0_686
	v_mbcnt_lo_u32_b32 v133, -1, 0
	v_mbcnt_hi_u32_b32 v133, -1, v133
	v_and_b32_e32 v133, 16, v133
	v_lshrrev_b32_e32 v132, 1, v133
	v_add_u32_e32 v132, v132, v133
	v_lshl_add_u32 v132, v190, 1, v132
	v_pk_mul_f32 v[126:127], v[126:127], v[188:189] op_sel_hi:[1,0]
	v_pk_mul_f32 v[128:129], v[128:129], v[188:189] op_sel_hi:[1,0]
	v_pk_mul_f32 v[122:123], v[122:123], v[188:189] op_sel_hi:[1,0]
	v_pk_mul_f32 v[124:125], v[124:125], v[188:189] op_sel_hi:[1,0]
	v_pk_mul_f32 v[118:119], v[118:119], v[188:189] op_sel_hi:[1,0]
	v_pk_mul_f32 v[120:121], v[120:121], v[188:189] op_sel_hi:[1,0]
	v_pk_mul_f32 v[114:115], v[114:115], v[188:189] op_sel_hi:[1,0]
	v_pk_mul_f32 v[116:117], v[116:117], v[188:189] op_sel_hi:[1,0]
	v_mul_lo_u32 v131, v186, s8
	v_cvt_pk_bf16_f32 v126, v126, v127
	v_cvt_pk_bf16_f32 v127, v128, v129
	v_cvt_pk_bf16_f32 v128, v122, v123
	v_cvt_pk_bf16_f32 v129, v124, v125
	v_cvt_pk_bf16_f32 v118, v118, v119
	v_cvt_pk_bf16_f32 v119, v120, v121
	v_cvt_pk_bf16_f32 v120, v114, v115
	v_cvt_pk_bf16_f32 v121, v116, v117
	v_add_u32_e32 v131, v131, v132
	v_permlane16_swap_b32_e32 v126, v128
	v_permlane16_swap_b32_e32 v127, v129
	v_permlane16_swap_b32_e32 v118, v120
	v_permlane16_swap_b32_e32 v119, v121
	global_store_dwordx4 v131, v[126:129], s[42:43]
	global_store_dwordx4 v131, v[118:121], s[42:43] offset:64
	v_pk_mul_f32 v[108:109], v[108:109], v[182:183] op_sel_hi:[1,0]
	v_pk_mul_f32 v[110:111], v[110:111], v[182:183] op_sel_hi:[1,0]
	v_pk_mul_f32 v[104:105], v[104:105], v[182:183] op_sel_hi:[1,0]
	v_pk_mul_f32 v[106:107], v[106:107], v[182:183] op_sel_hi:[1,0]
	v_pk_mul_f32 v[100:101], v[100:101], v[182:183] op_sel_hi:[1,0]
	v_pk_mul_f32 v[102:103], v[102:103], v[182:183] op_sel_hi:[1,0]
	v_pk_mul_f32 v[96:97], v[96:97], v[182:183] op_sel_hi:[1,0]
	v_pk_mul_f32 v[98:99], v[98:99], v[182:183] op_sel_hi:[1,0]
	v_mul_lo_u32 v131, v178, s8
	v_cvt_pk_bf16_f32 v108, v108, v109
	v_cvt_pk_bf16_f32 v109, v110, v111
	v_cvt_pk_bf16_f32 v110, v104, v105
	v_cvt_pk_bf16_f32 v111, v106, v107
	v_cvt_pk_bf16_f32 v100, v100, v101
	v_cvt_pk_bf16_f32 v101, v102, v103
	v_cvt_pk_bf16_f32 v102, v96, v97
	v_cvt_pk_bf16_f32 v103, v98, v99
	v_add_u32_e32 v131, v131, v132
	v_permlane16_swap_b32_e32 v108, v110
	v_permlane16_swap_b32_e32 v109, v111
	v_permlane16_swap_b32_e32 v100, v102
	v_permlane16_swap_b32_e32 v101, v103
	global_store_dwordx4 v131, v[108:111], s[42:43]
	global_store_dwordx4 v131, v[100:103], s[42:43] offset:64
	v_pk_mul_f32 v[92:93], v[92:93], v[180:181] op_sel_hi:[1,0]
	v_pk_mul_f32 v[94:95], v[94:95], v[180:181] op_sel_hi:[1,0]
	v_pk_mul_f32 v[88:89], v[88:89], v[180:181] op_sel_hi:[1,0]
	v_pk_mul_f32 v[90:91], v[90:91], v[180:181] op_sel_hi:[1,0]
	v_pk_mul_f32 v[84:85], v[84:85], v[180:181] op_sel_hi:[1,0]
	v_pk_mul_f32 v[86:87], v[86:87], v[180:181] op_sel_hi:[1,0]
	v_pk_mul_f32 v[80:81], v[80:81], v[180:181] op_sel_hi:[1,0]
	v_pk_mul_f32 v[82:83], v[82:83], v[180:181] op_sel_hi:[1,0]
	v_mul_lo_u32 v131, v174, s8
	v_cvt_pk_bf16_f32 v92, v92, v93
	v_cvt_pk_bf16_f32 v93, v94, v95
	v_cvt_pk_bf16_f32 v94, v88, v89
	v_cvt_pk_bf16_f32 v95, v90, v91
	v_cvt_pk_bf16_f32 v84, v84, v85
	v_cvt_pk_bf16_f32 v85, v86, v87
	v_cvt_pk_bf16_f32 v86, v80, v81
	v_cvt_pk_bf16_f32 v87, v82, v83
	v_add_u32_e32 v131, v131, v132
	v_permlane16_swap_b32_e32 v92, v94
	v_permlane16_swap_b32_e32 v93, v95
	v_permlane16_swap_b32_e32 v84, v86
	v_permlane16_swap_b32_e32 v85, v87
	global_store_dwordx4 v131, v[92:95], s[42:43]
	global_store_dwordx4 v131, v[84:87], s[42:43] offset:64
	v_pk_mul_f32 v[76:77], v[76:77], v[176:177] op_sel_hi:[1,0]
	v_pk_mul_f32 v[78:79], v[78:79], v[176:177] op_sel_hi:[1,0]
	v_pk_mul_f32 v[72:73], v[72:73], v[176:177] op_sel_hi:[1,0]
	v_pk_mul_f32 v[74:75], v[74:75], v[176:177] op_sel_hi:[1,0]
	v_pk_mul_f32 v[68:69], v[68:69], v[176:177] op_sel_hi:[1,0]
	v_pk_mul_f32 v[70:71], v[70:71], v[176:177] op_sel_hi:[1,0]
	v_pk_mul_f32 v[64:65], v[64:65], v[176:177] op_sel_hi:[1,0]
	v_pk_mul_f32 v[66:67], v[66:67], v[176:177] op_sel_hi:[1,0]
	v_mul_lo_u32 v131, v170, s8
	v_cvt_pk_bf16_f32 v76, v76, v77
	v_cvt_pk_bf16_f32 v77, v78, v79
	v_cvt_pk_bf16_f32 v78, v72, v73
	v_cvt_pk_bf16_f32 v79, v74, v75
	v_cvt_pk_bf16_f32 v68, v68, v69
	v_cvt_pk_bf16_f32 v69, v70, v71
	v_cvt_pk_bf16_f32 v70, v64, v65
	v_cvt_pk_bf16_f32 v71, v66, v67
	v_add_u32_e32 v131, v131, v132
	v_permlane16_swap_b32_e32 v76, v78
; template <int EPI>
; __device__ __forceinline__ void gemm_epilogue(const f32x4 (&acc)[2][2][4][2], const Unit& u, int wr, int wc, int fr, int fq,
;                                               const EpiArgs& ea, const float (&rs_pre)[2][4]) {
;     ...
;     if (plain) {
; #pragma unroll
;       for (int ai = 0; ai < 2; ++ai)
; #pragma unroll
;         for (int m = 0; m < 4; ++m) {
;           const int row = row0 + ai * 128 + m * 16;
;           const float rs = rsr[ai][m];
; #pragma unroll
;           for (int bj = 0; bj < 2; ++bj)
; #pragma unroll
;             for (int n = 0; n < 2; ++n)
;               *reinterpret_cast<uint2*>(ea.out_bf + (size_t)row * LD + lc0 + bj * 32 + n * 16) = pack4(acc[ai][bj][m][n] * rs);
;         }
	v_permlane16_swap_b32_e32 v77, v79
	v_permlane16_swap_b32_e32 v68, v70
	v_permlane16_swap_b32_e32 v69, v71
	global_store_dwordx4 v131, v[76:79], s[42:43]
	global_store_dwordx4 v131, v[68:71], s[42:43] offset:64
	v_pk_mul_f32 v[60:61], v[60:61], v[172:173] op_sel_hi:[1,0]
	v_pk_mul_f32 v[62:63], v[62:63], v[172:173] op_sel_hi:[1,0]
	v_pk_mul_f32 v[56:57], v[56:57], v[172:173] op_sel_hi:[1,0]
	v_pk_mul_f32 v[58:59], v[58:59], v[172:173] op_sel_hi:[1,0]
	v_pk_mul_f32 v[52:53], v[52:53], v[172:173] op_sel_hi:[1,0]
	v_pk_mul_f32 v[54:55], v[54:55], v[172:173] op_sel_hi:[1,0]
	v_pk_mul_f32 v[48:49], v[48:49], v[172:173] op_sel_hi:[1,0]
	v_pk_mul_f32 v[50:51], v[50:51], v[172:173] op_sel_hi:[1,0]
	v_mul_lo_u32 v131, v166, s8
	v_cvt_pk_bf16_f32 v60, v60, v61
	v_cvt_pk_bf16_f32 v61, v62, v63
	v_cvt_pk_bf16_f32 v62, v56, v57
	v_cvt_pk_bf16_f32 v63, v58, v59
	v_cvt_pk_bf16_f32 v52, v52, v53
	v_cvt_pk_bf16_f32 v53, v54, v55
	v_cvt_pk_bf16_f32 v54, v48, v49
	v_cvt_pk_bf16_f32 v55, v50, v51
	v_add_u32_e32 v131, v131, v132
	v_permlane16_swap_b32_e32 v60, v62
	v_permlane16_swap_b32_e32 v61, v63
	v_permlane16_swap_b32_e32 v52, v54
	v_permlane16_swap_b32_e32 v53, v55
	global_store_dwordx4 v131, v[60:63], s[42:43]
	global_store_dwordx4 v131, v[52:55], s[42:43] offset:64
	v_pk_mul_f32 v[44:45], v[44:45], v[168:169] op_sel_hi:[1,0]
	v_pk_mul_f32 v[46:47], v[46:47], v[168:169] op_sel_hi:[1,0]
	v_pk_mul_f32 v[40:41], v[40:41], v[168:169] op_sel_hi:[1,0]
	v_pk_mul_f32 v[42:43], v[42:43], v[168:169] op_sel_hi:[1,0]
	v_pk_mul_f32 v[36:37], v[36:37], v[168:169] op_sel_hi:[1,0]
	v_pk_mul_f32 v[38:39], v[38:39], v[168:169] op_sel_hi:[1,0]
	v_pk_mul_f32 v[32:33], v[32:33], v[168:169] op_sel_hi:[1,0]
	v_pk_mul_f32 v[34:35], v[34:35], v[168:169] op_sel_hi:[1,0]
	v_mul_lo_u32 v131, v162, s8
	v_cvt_pk_bf16_f32 v44, v44, v45
	v_cvt_pk_bf16_f32 v45, v46, v47
	v_cvt_pk_bf16_f32 v46, v40, v41
	v_cvt_pk_bf16_f32 v47, v42, v43
	v_cvt_pk_bf16_f32 v36, v36, v37
	v_cvt_pk_bf16_f32 v37, v38, v39
	v_cvt_pk_bf16_f32 v38, v32, v33
	v_cvt_pk_bf16_f32 v39, v34, v35
	v_add_u32_e32 v131, v131, v132
	v_permlane16_swap_b32_e32 v44, v46
	v_permlane16_swap_b32_e32 v45, v47
	v_permlane16_swap_b32_e32 v36, v38
	v_permlane16_swap_b32_e32 v37, v39
	global_store_dwordx4 v131, v[44:47], s[42:43]
	global_store_dwordx4 v131, v[36:39], s[42:43] offset:64
	v_pk_mul_f32 v[28:29], v[28:29], v[164:165] op_sel_hi:[1,0]
	v_pk_mul_f32 v[30:31], v[30:31], v[164:165] op_sel_hi:[1,0]
	v_pk_mul_f32 v[24:25], v[24:25], v[164:165] op_sel_hi:[1,0]
	v_pk_mul_f32 v[26:27], v[26:27], v[164:165] op_sel_hi:[1,0]
	v_pk_mul_f32 v[20:21], v[20:21], v[164:165] op_sel_hi:[1,0]
	v_pk_mul_f32 v[22:23], v[22:23], v[164:165] op_sel_hi:[1,0]
	v_pk_mul_f32 v[16:17], v[16:17], v[164:165] op_sel_hi:[1,0]
	v_pk_mul_f32 v[18:19], v[18:19], v[164:165] op_sel_hi:[1,0]
	v_mul_lo_u32 v131, v158, s8
	v_cvt_pk_bf16_f32 v28, v28, v29
	v_cvt_pk_bf16_f32 v29, v30, v31
	v_cvt_pk_bf16_f32 v30, v24, v25
	v_cvt_pk_bf16_f32 v31, v26, v27
	v_cvt_pk_bf16_f32 v20, v20, v21
	v_cvt_pk_bf16_f32 v21, v22, v23
	v_cvt_pk_bf16_f32 v22, v16, v17
	v_cvt_pk_bf16_f32 v23, v18, v19
	v_add_u32_e32 v131, v131, v132
	v_permlane16_swap_b32_e32 v28, v30
	v_permlane16_swap_b32_e32 v29, v31
	v_permlane16_swap_b32_e32 v20, v22
	v_permlane16_swap_b32_e32 v21, v23
	global_store_dwordx4 v131, v[28:31], s[42:43]
	global_store_dwordx4 v131, v[20:23], s[42:43] offset:64
	v_pk_mul_f32 v[12:13], v[12:13], v[160:161] op_sel_hi:[1,0]
	v_pk_mul_f32 v[14:15], v[14:15], v[160:161] op_sel_hi:[1,0]
	v_pk_mul_f32 v[8:9], v[8:9], v[160:161] op_sel_hi:[1,0]
	v_pk_mul_f32 v[10:11], v[10:11], v[160:161] op_sel_hi:[1,0]
	v_pk_mul_f32 v[4:5], v[4:5], v[160:161] op_sel_hi:[1,0]
	v_pk_mul_f32 v[6:7], v[6:7], v[160:161] op_sel_hi:[1,0]
	v_pk_mul_f32 v[0:1], v[0:1], v[160:161] op_sel_hi:[1,0]
	v_pk_mul_f32 v[2:3], v[2:3], v[160:161] op_sel_hi:[1,0]
	v_mul_lo_u32 v131, v156, s8
	v_cvt_pk_bf16_f32 v12, v12, v13
	v_cvt_pk_bf16_f32 v13, v14, v15
	v_cvt_pk_bf16_f32 v14, v8, v9
	v_cvt_pk_bf16_f32 v15, v10, v11
	v_cvt_pk_bf16_f32 v4, v4, v5
	v_cvt_pk_bf16_f32 v5, v6, v7
	v_cvt_pk_bf16_f32 v6, v0, v1
	v_cvt_pk_bf16_f32 v7, v2, v3
	v_add_u32_e32 v131, v131, v132
	v_permlane16_swap_b32_e32 v12, v14
	v_permlane16_swap_b32_e32 v13, v15
	v_permlane16_swap_b32_e32 v4, v6
	v_permlane16_swap_b32_e32 v5, v7
	global_store_dwordx4 v131, v[12:15], s[42:43]
	global_store_dwordx4 v131, v[4:7], s[42:43] offset:64
	s_branch .LBB0_686
